# P0: GEMV silu staging loop (20 serial load+wait iterations with kernarg reloads) and the bf16 conversion loop now issue all their loads up front
# speedup vs baseline: 1.0076x; 1.0076x over previous
.LBB0_26:
	s_movk_i32 s4, 0x400
	v_cmp_gt_i32_e32 vcc, s4, v15
	s_and_saveexec_b64 s[6:7], vcc
	s_cbranch_execz .LBB0_29
	s_cmpk_lt_u32 s65, 0xa80
	s_cselect_b64 s[8:9], -1, 0
	s_and_b64 s[8:9], s[8:9], exec
	s_load_dwordx16 s[8:23], s[86:87], 0x0
	s_movk_i32 s4, 0xf5c0
	s_cselect_b32 s4, s4, 0xfffff580
	v_lshlrev_b32_e32 v6, 2, v15
	v_ashrrev_i32_e32 v7, 31, v6
	s_waitcnt lgkmcnt(0)
	s_cselect_b32 s28, s15, s19
	s_cselect_b32 s29, s14, s18
	s_load_dwordx16 s[12:27], s[86:87], 0x100
	s_waitcnt lgkmcnt(0)
	s_mov_b64 s[8:9], s[68:69]
	s_mov_b64 s[10:11], s[70:71]
	s_mov_b64 s[12:13], s[72:73]
	s_mov_b64 s[14:15], s[74:75]
	s_mov_b64 s[16:17], s[76:77]
	s_mov_b64 s[18:19], s[78:79]
	s_mov_b64 s[20:21], s[80:81]
	s_mov_b64 s[22:23], s[82:83]
	s_load_dwordx16 s[68:83], s[86:87], 0x140
	v_add_u32_e32 v1, 0xfffffc00, v6
	s_waitcnt lgkmcnt(0)
	s_cselect_b32 s24, s27, s71
	s_cselect_b32 s25, s26, s70
	s_mov_b64 s[82:83], s[22:23]
	s_add_i32 s4, s65, s4
	s_mov_b64 s[80:81], s[20:21]
	s_mov_b64 s[78:79], s[18:19]
	s_mov_b64 s[76:77], s[16:17]
	s_mov_b64 s[74:75], s[14:15]
	s_mov_b64 s[72:73], s[12:13]
	s_mov_b64 s[70:71], s[10:11]
	s_mov_b64 s[68:69], s[8:9]
	s_lshl_b64 s[8:9], s[4:5], 13
	s_add_u32 s8, s25, s8
	s_addc_u32 s9, s24, s9
	v_lshl_add_u64 v[4:5], v[6:7], 1, s[8:9]
	s_lshl_b64 s[8:9], s[4:5], 14
	s_add_u32 s8, s29, s8
	s_addc_u32 s9, s28, s9
	v_lshl_add_u64 v[6:7], v[6:7], 2, s[8:9]
	v_lshl_add_u64 v[4:5], v[4:5], 0, 4
	v_lshl_add_u64 v[6:7], v[6:7], 0, 8
	s_mov_b64 s[8:9], 0
	global_load_dwordx4 v[210:213], v[6:7], off offset:-8
	s_mov_b64 s[10:11], 0x1000
	s_mov_b64 s[12:13], 0x800
	v_lshl_add_u64 v[226:227], v[6:7], 0, s[10:11]
	global_load_dwordx4 v[214:217], v[226:227], off offset:-8
	v_lshl_add_u64 v[226:227], v[226:227], 0, s[10:11]
	global_load_dwordx4 v[218:221], v[226:227], off offset:-8
	v_lshl_add_u64 v[226:227], v[226:227], 0, s[10:11]
	global_load_dwordx4 v[222:225], v[226:227], off offset:-8
	s_waitcnt vmcnt(3)
	v_cvt_pk_bf16_f32 v8, v210, v211
	v_cvt_pk_bf16_f32 v9, v212, v213
	global_store_dwordx2 v[4:5], v[8:9], off offset:-4
	v_lshl_add_u64 v[4:5], v[4:5], 0, s[12:13]
	s_waitcnt vmcnt(3)
	v_cvt_pk_bf16_f32 v8, v214, v215
	v_cvt_pk_bf16_f32 v9, v216, v217
	global_store_dwordx2 v[4:5], v[8:9], off offset:-4
	v_lshl_add_u64 v[4:5], v[4:5], 0, s[12:13]
	s_waitcnt vmcnt(3)
	v_cvt_pk_bf16_f32 v8, v218, v219
	v_cvt_pk_bf16_f32 v9, v220, v221
	global_store_dwordx2 v[4:5], v[8:9], off offset:-4
	v_lshl_add_u64 v[4:5], v[4:5], 0, s[12:13]
	s_waitcnt vmcnt(3)
	v_cvt_pk_bf16_f32 v8, v222, v223
	v_cvt_pk_bf16_f32 v9, v224, v225
	global_store_dwordx2 v[4:5], v[8:9], off offset:-4
	v_lshl_add_u64 v[4:5], v[4:5], 0, s[12:13]

.LBB0_45:
	s_movk_i32 s4, 0x1400
	v_cmp_gt_i32_e32 vcc, s4, v15
	s_and_saveexec_b64 s[6:7], vcc
	s_cbranch_execz .LBB0_52
	s_load_dwordx2 s[8:9], s[86:87], 0x48
	s_load_dwordx2 s[10:11], s[86:87], 0x10
	v_lshlrev_b32_e32 v1, 2, v15
	v_add_u32_e32 v4, 0x1000, v1
	v_add_u32_e32 v5, 0x2000, v1
	v_add_u32_e32 v6, 0x3000, v1
	s_waitcnt lgkmcnt(0)
	global_load_dword v210, v1, s[8:9]
	global_load_dword v211, v1, s[8:9] offset:1024
	global_load_dword v212, v1, s[8:9] offset:2048
	global_load_dword v213, v1, s[8:9] offset:3072
	global_load_dword v214, v1, s[10:11]
	global_load_dword v215, v1, s[10:11] offset:1024
	global_load_dword v216, v1, s[10:11] offset:2048
	global_load_dword v217, v1, s[10:11] offset:3072
	global_load_dword v218, v4, s[10:11]
	global_load_dword v219, v4, s[10:11] offset:1024
	global_load_dword v220, v4, s[10:11] offset:2048
	global_load_dword v221, v4, s[10:11] offset:3072
	global_load_dword v222, v5, s[10:11]
	global_load_dword v223, v5, s[10:11] offset:1024
	global_load_dword v224, v5, s[10:11] offset:2048
	global_load_dword v225, v5, s[10:11] offset:3072
	global_load_dword v226, v6, s[10:11]
	global_load_dword v227, v6, s[10:11] offset:1024
	global_load_dword v228, v6, s[10:11] offset:2048
	global_load_dword v229, v6, s[10:11] offset:3072
	s_waitcnt vmcnt(16)
	v_mul_f32_e32 v230, 0xbfb8aa3b, v210
	v_mul_f32_e32 v231, 0xbfb8aa3b, v211
	v_mul_f32_e32 v232, 0xbfb8aa3b, v212
	v_mul_f32_e32 v233, 0xbfb8aa3b, v213
	v_exp_f32_e32 v230, v230
	v_exp_f32_e32 v231, v231
	v_exp_f32_e32 v232, v232
	v_exp_f32_e32 v233, v233
	v_add_f32_e32 v230, 1.0, v230
	v_add_f32_e32 v231, 1.0, v231
	v_add_f32_e32 v232, 1.0, v232
	v_add_f32_e32 v233, 1.0, v233
	v_rcp_f32_e32 v230, v230
	v_rcp_f32_e32 v231, v231
	v_rcp_f32_e32 v232, v232
	v_rcp_f32_e32 v233, v233
	v_mul_f32_e32 v210, v210, v230
	v_mul_f32_e32 v211, v211, v231
	v_mul_f32_e32 v212, v212, v232
	v_mul_f32_e32 v213, v213, v233
	ds_write_b32 v1, v210
	ds_write_b32 v1, v211 offset:1024
	ds_write_b32 v1, v212 offset:2048
	ds_write_b32 v1, v213 offset:3072
	s_waitcnt vmcnt(12)
	v_mul_f32_e32 v230, 0xbfb8aa3b, v214
	v_mul_f32_e32 v231, 0xbfb8aa3b, v215
	v_mul_f32_e32 v232, 0xbfb8aa3b, v216
	v_mul_f32_e32 v233, 0xbfb8aa3b, v217
	v_exp_f32_e32 v230, v230
	v_exp_f32_e32 v231, v231
	v_exp_f32_e32 v232, v232
	v_exp_f32_e32 v233, v233
	v_add_f32_e32 v230, 1.0, v230
	v_add_f32_e32 v231, 1.0, v231
	v_add_f32_e32 v232, 1.0, v232
	v_add_f32_e32 v233, 1.0, v233
	v_rcp_f32_e32 v230, v230
	v_rcp_f32_e32 v231, v231
	v_rcp_f32_e32 v232, v232
	v_rcp_f32_e32 v233, v233
	v_mul_f32_e32 v214, v214, v230
	v_mul_f32_e32 v215, v215, v231
	v_mul_f32_e32 v216, v216, v232
	v_mul_f32_e32 v217, v217, v233
	ds_write_b32 v1, v214 offset:4096
	ds_write_b32 v1, v215 offset:5120
	ds_write_b32 v1, v216 offset:6144
	ds_write_b32 v1, v217 offset:7168
	s_waitcnt vmcnt(8)
	v_mul_f32_e32 v230, 0xbfb8aa3b, v218
	v_mul_f32_e32 v231, 0xbfb8aa3b, v219
	v_mul_f32_e32 v232, 0xbfb8aa3b, v220
	v_mul_f32_e32 v233, 0xbfb8aa3b, v221
	v_exp_f32_e32 v230, v230
	v_exp_f32_e32 v231, v231
	v_exp_f32_e32 v232, v232
	v_exp_f32_e32 v233, v233
	v_add_f32_e32 v230, 1.0, v230
	v_add_f32_e32 v231, 1.0, v231
	v_add_f32_e32 v232, 1.0, v232
	v_add_f32_e32 v233, 1.0, v233
	v_rcp_f32_e32 v230, v230
	v_rcp_f32_e32 v231, v231
	v_rcp_f32_e32 v232, v232
	v_rcp_f32_e32 v233, v233
	v_mul_f32_e32 v218, v218, v230
	v_mul_f32_e32 v219, v219, v231
	v_mul_f32_e32 v220, v220, v232
	v_mul_f32_e32 v221, v221, v233
	ds_write_b32 v1, v218 offset:8192
	ds_write_b32 v1, v219 offset:9216
	ds_write_b32 v1, v220 offset:10240
	ds_write_b32 v1, v221 offset:11264
	s_waitcnt vmcnt(4)
	v_mul_f32_e32 v230, 0xbfb8aa3b, v222
	v_mul_f32_e32 v231, 0xbfb8aa3b, v223
	v_mul_f32_e32 v232, 0xbfb8aa3b, v224
	v_mul_f32_e32 v233, 0xbfb8aa3b, v225
	v_exp_f32_e32 v230, v230
	v_exp_f32_e32 v231, v231
	v_exp_f32_e32 v232, v232
	v_exp_f32_e32 v233, v233
	v_add_f32_e32 v230, 1.0, v230
	v_add_f32_e32 v231, 1.0, v231
	v_add_f32_e32 v232, 1.0, v232
	v_add_f32_e32 v233, 1.0, v233
	v_rcp_f32_e32 v230, v230
	v_rcp_f32_e32 v231, v231
	v_rcp_f32_e32 v232, v232
	v_rcp_f32_e32 v233, v233
	v_mul_f32_e32 v222, v222, v230
	v_mul_f32_e32 v223, v223, v231
	v_mul_f32_e32 v224, v224, v232
	v_mul_f32_e32 v225, v225, v233
	ds_write_b32 v1, v222 offset:12288
	ds_write_b32 v1, v223 offset:13312
	ds_write_b32 v1, v224 offset:14336
	ds_write_b32 v1, v225 offset:15360
	s_waitcnt vmcnt(0)
	v_mul_f32_e32 v230, 0xbfb8aa3b, v226
	v_mul_f32_e32 v231, 0xbfb8aa3b, v227
	v_mul_f32_e32 v232, 0xbfb8aa3b, v228
	v_mul_f32_e32 v233, 0xbfb8aa3b, v229
	v_exp_f32_e32 v230, v230
	v_exp_f32_e32 v231, v231
	v_exp_f32_e32 v232, v232
	v_exp_f32_e32 v233, v233
	v_add_f32_e32 v230, 1.0, v230
	v_add_f32_e32 v231, 1.0, v231
	v_add_f32_e32 v232, 1.0, v232
	v_add_f32_e32 v233, 1.0, v233
	v_rcp_f32_e32 v230, v230
	v_rcp_f32_e32 v231, v231
	v_rcp_f32_e32 v232, v232
	v_rcp_f32_e32 v233, v233
	v_mul_f32_e32 v226, v226, v230
	v_mul_f32_e32 v227, v227, v231
	v_mul_f32_e32 v228, v228, v232
	v_mul_f32_e32 v229, v229, v233
	ds_write_b32 v1, v226 offset:16384
	ds_write_b32 v1, v227 offset:17408
	ds_write_b32 v1, v228 offset:18432
	ds_write_b32 v1, v229 offset:19456
